# layer-0 attention: the epilogue's silu-gate loads are issued early (stick-breaking: with the q loads; MLA: before the last key tile), on top of the MLA tile-loop rewrite
# speedup vs baseline: 1.0114x; 1.0047x over previous
.LBB0_794:
	v_ashrrev_i32_e32 v253, 31, v180
	v_mov_b32_e32 v252, v180
	v_mov_b64_e32 v[254:255], s[92:93]
	v_lshl_add_u64 v[252:253], v[252:253], 0, s[12:13]
	v_mad_u64_u32 v[254:255], vcc, v252, s45, v[254:255]
	v_mad_i32_i24 v255, v253, s45, v255
	v_mov_b32_e32 v252, s9
	v_add_co_u32_e32 v254, vcc, s10, v254
	v_mov_b32_e32 v253, v17
	v_addc_co_u32_e32 v255, vcc, v252, v255, vcc
	v_mov_b32_e32 v252, v178
	v_lshl_add_u64 v[254:255], v[254:255], 0, v[252:253]
	v_add_co_u32_e32 v254, vcc, 0x1340, v254
	s_nop 0
	v_addc_co_u32_e32 v255, vcc, 0, v255, vcc
	global_load_dwordx4 v[238:241], v[254:255], off
	global_load_dwordx4 v[242:245], v[254:255], off offset:32
	global_load_dwordx4 v[248:251], v[254:255], off offset:64
	global_load_dwordx4 v[252:255], v[254:255], off offset:96
	s_lshl_b32 s0, s49, 6
	s_sub_i32 s0, s0, 64
	s_lshr_b32 s24, s0, 5
	s_cmp_gt_u32 s24, s11
	s_cbranch_scc1 .LBB0_819
	ds_read_b128 v[128:131], v177
	ds_read_b128 v[132:135], v177 offset:32
	ds_read_b128 v[136:139], v177 offset:64
	ds_read_b128 v[184:187], v177 offset:96
	ds_read_b128 v[188:191], v177 offset:128
	ds_read_b128 v[192:195], v177 offset:160
	s_cmp_ge_u32 s24, s11
	s_cselect_b64 s[0:1], -1, 0
	s_cmp_lt_u32 s24, s11
	s_cselect_b64 s[30:31], -1, 0
	v_xor_b32_e32 v84, 0x80000000, v182
	v_mov_b32_e32 v85, v84
	v_mov_b32_e32 v86, v84
	v_mov_b32_e32 v87, v84
	v_mov_b32_e32 v88, v84
	v_mov_b32_e32 v89, v84
	v_mov_b32_e32 v90, v84
	v_mov_b32_e32 v91, v84
	v_mov_b32_e32 v92, v84
	v_mov_b32_e32 v93, v84
	v_mov_b32_e32 v94, v84
	v_mov_b32_e32 v95, v84
	v_mov_b32_e32 v96, v84
	v_mov_b32_e32 v97, v84
	v_mov_b32_e32 v98, v84
	v_mov_b32_e32 v99, v84
	s_and_b64 vcc, exec, s[0:1]
	s_waitcnt lgkmcnt(5)
	v_mfma_f32_32x32x16_bf16 v[18:33], v[128:131], v[124:127], v[84:99]
	s_waitcnt lgkmcnt(4)
	v_mfma_f32_32x32x16_bf16 v[18:33], v[132:135], v[120:123], v[18:33]
	s_waitcnt lgkmcnt(3)
	v_mfma_f32_32x32x16_bf16 v[18:33], v[136:139], v[116:119], v[18:33]
	s_waitcnt lgkmcnt(2)
	v_mfma_f32_32x32x16_bf16 v[18:33], v[184:187], v[112:115], v[18:33]
	s_waitcnt lgkmcnt(1)
	v_mfma_f32_32x32x16_bf16 v[18:33], v[188:191], v[108:111], v[18:33]
	s_waitcnt lgkmcnt(0)
	v_mfma_f32_32x32x16_bf16 v[18:33], v[192:195], v[104:107], v[18:33]
	s_cbranch_vccnz .LBB0_797
	ds_read_b128 v[34:37], v177 offset:6656
	ds_read_b128 v[38:41], v177 offset:6688
	ds_read_b128 v[42:45], v177 offset:6720
	ds_read_b128 v[46:49], v177 offset:6752
	ds_read_b128 v[128:131], v177 offset:6784
	ds_read_b128 v[132:135], v177 offset:6816
	s_waitcnt lgkmcnt(5)
	v_mfma_f32_32x32x16_bf16 v[84:99], v[34:37], v[124:127], v[84:99]
	s_waitcnt lgkmcnt(4)
	v_mfma_f32_32x32x16_bf16 v[84:99], v[38:41], v[120:123], v[84:99]
	s_waitcnt lgkmcnt(3)
	v_mfma_f32_32x32x16_bf16 v[84:99], v[42:45], v[116:119], v[84:99]
	s_waitcnt lgkmcnt(2)
	v_mfma_f32_32x32x16_bf16 v[84:99], v[46:49], v[112:115], v[84:99]
	s_waitcnt lgkmcnt(1)
	v_mfma_f32_32x32x16_bf16 v[84:99], v[128:131], v[108:111], v[84:99]
	s_waitcnt lgkmcnt(0)
	v_mfma_f32_32x32x16_bf16 v[84:99], v[132:135], v[104:107], v[84:99]
	s_nop 11
	v_mov_b32_e32 v34, v84
	v_mov_b32_e32 v35, v85
	v_mov_b32_e32 v36, v86
	v_mov_b32_e32 v37, v87
	v_mov_b32_e32 v38, v88
	v_mov_b32_e32 v39, v89
	v_mov_b32_e32 v40, v90
	v_mov_b32_e32 v41, v91
	v_mov_b32_e32 v42, v92
	v_mov_b32_e32 v43, v93
	v_mov_b32_e32 v44, v94
	v_mov_b32_e32 v45, v95
	v_mov_b32_e32 v46, v96
	v_mov_b32_e32 v47, v97
	v_mov_b32_e32 v48, v98
	v_mov_b32_e32 v49, v99

.LBB0_819:
	v_mov_b32_e32 v2, v183
	v_mov_b32_e32 v3, v183
	s_nop 1
	v_permlane32_swap_b32_e32 v2, v3
	v_cndmask_b32_e64 v2, v2, v3, s[6:7]
	v_add_f32_e32 v2, v183, v2
	v_div_scale_f32 v3, s[0:1], v2, v2, 1.0
	v_rcp_f32_e32 v4, v3
	s_barrier
	v_fma_f32 v5, -v3, v4, 1.0
	v_fmac_f32_e32 v4, v5, v4
	v_div_scale_f32 v5, vcc, 1.0, v2, 1.0
	v_mul_f32_e32 v6, v5, v4
	v_fma_f32 v7, -v3, v6, v5
	v_fmac_f32_e32 v6, v7, v4
	v_fma_f32 v3, -v3, v6, v5
	v_div_fmas_f32 v3, v3, v4, v6
	v_ashrrev_i32_e32 v181, 31, v180
	v_div_fixup_f32 v16, v3, v2, 1.0
	v_lshl_add_u64 v[2:3], v[180:181], 0, s[12:13]
	v_mov_b64_e32 v[4:5], s[92:93]
	v_mad_u64_u32 v[4:5], s[0:1], v2, s45, v[4:5]
	v_mad_i32_i24 v5, v3, s45, v5
	s_mov_b32 s11, s9
	v_lshl_add_u64 v[4:5], v[4:5], 0, s[10:11]
	v_lshlrev_b64 v[2:3], 11, v[2:3]
	v_mov_b32_e32 v179, v17
	v_lshl_add_u64 v[22:23], s[20:21], 0, v[2:3]
	v_lshl_add_u64 v[2:3], v[4:5], 0, v[178:179]
	s_mov_b64 s[0:1], 0x1340
	v_lshl_add_u64 v[4:5], v[2:3], 0, s[0:1]
	s_movk_i32 s0, 0x1000
	v_add_co_u32_e32 v2, vcc, s0, v2
	v_mul_f32_e32 v24, v68, v16
	s_nop 0
	v_addc_co_u32_e32 v3, vcc, 0, v3, vcc
	s_waitcnt vmcnt(0)
	v_mov_b32_e32 v18, v238
	v_mov_b32_e32 v19, v239
	v_mov_b32_e32 v20, v240
	v_mov_b32_e32 v21, v241
	v_mov_b32_e32 v10, v242
	v_mov_b32_e32 v11, v243
	v_mov_b32_e32 v12, v244
	v_mov_b32_e32 v13, v245
	v_mov_b32_e32 v6, v248
	v_mov_b32_e32 v7, v249
	v_mov_b32_e32 v8, v250
	v_mov_b32_e32 v9, v251
	s_nop 0
	v_mov_b32_e32 v2, v252
	v_mov_b32_e32 v3, v253
	v_mov_b32_e32 v4, v254
	v_mov_b32_e32 v5, v255
	v_mul_f32_e32 v28, v72, v16
	v_mul_f32_e32 v25, v69, v16
	v_mul_f32_e32 v29, v73, v16
	v_mul_f32_e32 v30, v70, v16
	v_mul_f32_e32 v26, v74, v16
	v_mul_f32_e32 v31, v71, v16
	v_mul_f32_e32 v27, v75, v16
	v_permlane32_swap_b32_e32 v24, v28
	v_permlane32_swap_b32_e32 v25, v29
	v_permlane32_swap_b32_e32 v30, v26
	v_permlane32_swap_b32_e32 v31, v27
	v_lshl_add_u64 v[22:23], v[22:23], 0, s[10:11]
	v_lshl_add_u64 v[22:23], v[22:23], 0, v[178:179]
	s_mov_b64 s[0:1], 0xf60400
	v_lshl_add_u64 v[84:85], v[22:23], 0, s[0:1]
	s_mov_b32 s0, 0xf60000
	v_mul_f32_e32 v44, v66, v16
	s_waitcnt vmcnt(3)
	v_lshlrev_b32_e32 v32, 16, v18
	v_and_b32_e32 v33, 0xffff0000, v18
	v_mul_f32_e32 v18, 0xbfb8aa3b, v32
	v_exp_f32_e32 v18, v18
	v_pk_mul_f32 v[24:25], v[32:33], v[24:25]
	v_add_f32_e32 v18, 1.0, v18
	v_rcp_f32_e32 v34, v18
	v_mul_f32_e32 v18, 0xbfb8aa3b, v33
	v_exp_f32_e32 v18, v18
	s_nop 0
	v_add_f32_e32 v18, 1.0, v18
	v_rcp_f32_e32 v35, v18
	v_lshlrev_b32_e32 v18, 16, v19
	v_and_b32_e32 v19, 0xffff0000, v19
	v_mul_f32_e32 v32, 0xbfb8aa3b, v18
	v_pk_mul_f32 v[30:31], v[18:19], v[30:31]
	v_mul_f32_e32 v18, 0xbfb8aa3b, v19
	v_exp_f32_e32 v32, v32
	v_exp_f32_e32 v18, v18
	v_pk_mul_f32 v[24:25], v[24:25], v[34:35]
	v_add_f32_e32 v32, 1.0, v32
	v_add_f32_e32 v18, 1.0, v18
	v_rcp_f32_e32 v32, v32
	v_rcp_f32_e32 v33, v18
	v_cvt_pk_bf16_f32 v24, v24, v25
	v_pk_mul_f32 v[18:19], v[32:33], v[30:31]
	v_lshlrev_b32_e32 v30, 16, v20
	v_and_b32_e32 v31, 0xffff0000, v20
	v_mul_f32_e32 v20, 0xbfb8aa3b, v30
	v_exp_f32_e32 v20, v20
	v_pk_mul_f32 v[28:29], v[30:31], v[28:29]
	v_cvt_pk_bf16_f32 v25, v18, v19
	v_add_co_u32_e32 v18, vcc, s0, v22
	v_add_f32_e32 v20, 1.0, v20
	v_rcp_f32_e32 v32, v20
	v_mul_f32_e32 v20, 0xbfb8aa3b, v31
	v_exp_f32_e32 v20, v20
	v_addc_co_u32_e32 v19, vcc, 0, v23, vcc
	v_mul_f32_e32 v22, v78, v16
	v_add_f32_e32 v20, 1.0, v20
	v_rcp_f32_e32 v33, v20
	v_lshlrev_b32_e32 v20, 16, v21
	v_and_b32_e32 v21, 0xffff0000, v21
	v_mul_f32_e32 v30, 0xbfb8aa3b, v20
	v_pk_mul_f32 v[26:27], v[20:21], v[26:27]
	v_mul_f32_e32 v20, 0xbfb8aa3b, v21
	v_exp_f32_e32 v30, v30
	v_exp_f32_e32 v20, v20
	v_pk_mul_f32 v[28:29], v[28:29], v[32:33]
	v_mul_f32_e32 v23, v79, v16
	v_add_f32_e32 v30, 1.0, v30
	v_add_f32_e32 v20, 1.0, v20
	v_rcp_f32_e32 v30, v30
	v_rcp_f32_e32 v31, v20
	s_mov_b64 s[0:1], 0
	v_pk_mul_f32 v[20:21], v[30:31], v[26:27]
	v_cvt_pk_bf16_f32 v26, v28, v29
	v_cvt_pk_bf16_f32 v27, v20, v21
	global_store_dwordx4 v[18:19], v[24:27], off offset:1024
	v_mul_f32_e32 v18, v76, v16
	v_mul_f32_e32 v20, v80, v16
	s_waitcnt vmcnt(3)
	v_lshlrev_b32_e32 v26, 16, v10
	v_and_b32_e32 v27, 0xffff0000, v10
	v_mul_f32_e32 v10, 0xbfb8aa3b, v26
	v_exp_f32_e32 v10, v10
	v_mul_f32_e32 v19, v77, v16
	v_mul_f32_e32 v21, v81, v16
	v_mul_f32_e32 v24, v82, v16
	v_add_f32_e32 v10, 1.0, v10
	v_rcp_f32_e32 v28, v10
	v_mul_f32_e32 v10, 0xbfb8aa3b, v27
	v_exp_f32_e32 v10, v10
	v_mul_f32_e32 v25, v83, v16
	v_permlane32_swap_b32_e32 v18, v20
	v_add_f32_e32 v10, 1.0, v10
	v_permlane32_swap_b32_e32 v19, v21
	v_permlane32_swap_b32_e32 v22, v24
	v_permlane32_swap_b32_e32 v23, v25
	v_rcp_f32_e32 v29, v10
	v_lshlrev_b32_e32 v10, 16, v11
	v_and_b32_e32 v11, 0xffff0000, v11
	v_pk_mul_f32 v[18:19], v[26:27], v[18:19]
	v_mul_f32_e32 v26, 0xbfb8aa3b, v10
	v_pk_mul_f32 v[22:23], v[10:11], v[22:23]
	v_mul_f32_e32 v10, 0xbfb8aa3b, v11
	v_exp_f32_e32 v10, v10
	v_exp_f32_e32 v26, v26
	v_and_b32_e32 v11, 0xffff0000, v12
	v_pk_mul_f32 v[18:19], v[28:29], v[18:19]
	v_add_f32_e32 v10, 1.0, v10
	v_rcp_f32_e32 v27, v10
	v_lshlrev_b32_e32 v10, 16, v12
	v_mul_f32_e32 v12, 0xbfb8aa3b, v10
	v_pk_mul_f32 v[20:21], v[10:11], v[20:21]
	v_mul_f32_e32 v10, 0xbfb8aa3b, v11
	v_add_f32_e32 v26, 1.0, v26
	v_exp_f32_e32 v10, v10
	v_rcp_f32_e32 v26, v26
	v_exp_f32_e32 v12, v12
	v_and_b32_e32 v11, 0xffff0000, v13
	v_add_f32_e32 v10, 1.0, v10
	v_pk_mul_f32 v[22:23], v[26:27], v[22:23]
	v_add_f32_e32 v12, 1.0, v12
	v_rcp_f32_e32 v27, v10
	v_lshlrev_b32_e32 v10, 16, v13
	v_rcp_f32_e32 v26, v12
	v_mul_f32_e32 v12, 0xbfb8aa3b, v10
	v_pk_mul_f32 v[24:25], v[10:11], v[24:25]
	v_mul_f32_e32 v10, 0xbfb8aa3b, v11
	v_exp_f32_e32 v12, v12
	v_exp_f32_e32 v10, v10
	v_cvt_pk_bf16_f32 v11, v22, v23
	s_waitcnt vmcnt(2)
	v_lshlrev_b32_e32 v22, 16, v6
	v_add_f32_e32 v12, 1.0, v12
	v_add_f32_e32 v10, 1.0, v10
	v_and_b32_e32 v23, 0xffff0000, v6
	v_mul_f32_e32 v6, 0xbfb8aa3b, v22
	v_rcp_f32_e32 v12, v12
	v_rcp_f32_e32 v13, v10
	v_exp_f32_e32 v6, v6
	v_pk_mul_f32 v[20:21], v[26:27], v[20:21]
	v_cvt_pk_bf16_f32 v10, v18, v19
	v_pk_mul_f32 v[24:25], v[12:13], v[24:25]
	v_add_f32_e32 v6, 1.0, v6
	v_cvt_pk_bf16_f32 v13, v24, v25
	v_rcp_f32_e32 v24, v6
	v_mul_f32_e32 v6, 0xbfb8aa3b, v23
	v_exp_f32_e32 v6, v6
	v_cvt_pk_bf16_f32 v12, v20, v21
	global_store_dwordx4 v[84:85], v[10:13], off offset:32
	v_mul_f32_e32 v18, v54, v16
	v_mul_f32_e32 v20, v58, v16
	v_mul_f32_e32 v10, v52, v16
	v_mul_f32_e32 v12, v56, v16
	v_mul_f32_e32 v11, v53, v16
	v_mul_f32_e32 v13, v57, v16
	v_mul_f32_e32 v19, v55, v16
	v_mul_f32_e32 v21, v59, v16
	v_add_f32_e32 v6, 1.0, v6
	v_permlane32_swap_b32_e32 v10, v12
	v_permlane32_swap_b32_e32 v11, v13
	v_permlane32_swap_b32_e32 v18, v20
	v_permlane32_swap_b32_e32 v19, v21
	v_rcp_f32_e32 v25, v6
	v_lshlrev_b32_e32 v6, 16, v7
	v_and_b32_e32 v7, 0xffff0000, v7
	v_pk_mul_f32 v[10:11], v[22:23], v[10:11]
	v_mul_f32_e32 v22, 0xbfb8aa3b, v6
	v_pk_mul_f32 v[18:19], v[6:7], v[18:19]
	v_mul_f32_e32 v6, 0xbfb8aa3b, v7
	v_exp_f32_e32 v6, v6
	v_exp_f32_e32 v22, v22
	v_and_b32_e32 v7, 0xffff0000, v8
	v_pk_mul_f32 v[10:11], v[24:25], v[10:11]
	v_add_f32_e32 v6, 1.0, v6
	v_rcp_f32_e32 v23, v6
	v_lshlrev_b32_e32 v6, 16, v8
	v_mul_f32_e32 v8, 0xbfb8aa3b, v6
	v_pk_mul_f32 v[12:13], v[6:7], v[12:13]
	v_mul_f32_e32 v6, 0xbfb8aa3b, v7
	v_add_f32_e32 v22, 1.0, v22
	v_exp_f32_e32 v6, v6
	v_rcp_f32_e32 v22, v22
	v_exp_f32_e32 v8, v8
	v_and_b32_e32 v7, 0xffff0000, v9
	v_add_f32_e32 v6, 1.0, v6
	v_pk_mul_f32 v[18:19], v[22:23], v[18:19]
	v_add_f32_e32 v8, 1.0, v8
	v_rcp_f32_e32 v23, v6
	v_lshlrev_b32_e32 v6, 16, v9
	v_rcp_f32_e32 v22, v8
	v_mul_f32_e32 v8, 0xbfb8aa3b, v6
	v_pk_mul_f32 v[20:21], v[6:7], v[20:21]
	v_mul_f32_e32 v6, 0xbfb8aa3b, v7
	v_exp_f32_e32 v8, v8
	v_exp_f32_e32 v6, v6
	v_pk_mul_f32 v[12:13], v[22:23], v[12:13]
	v_cvt_pk_bf16_f32 v7, v18, v19
	v_add_f32_e32 v8, 1.0, v8
	v_add_f32_e32 v6, 1.0, v6
	v_rcp_f32_e32 v8, v8
	v_rcp_f32_e32 v9, v6
	v_cvt_pk_bf16_f32 v6, v10, v11
	v_mul_f32_e32 v26, v60, v16
	v_mul_f32_e32 v27, v61, v16
	v_pk_mul_f32 v[20:21], v[8:9], v[20:21]
	v_cvt_pk_bf16_f32 v8, v12, v13
	v_cvt_pk_bf16_f32 v9, v20, v21
	global_store_dwordx4 v[84:85], v[6:9], off offset:64
	v_mul_f32_e32 v28, v62, v16
	v_mul_f32_e32 v29, v63, v16
	v_mul_f32_e32 v6, v64, v16
	v_mul_f32_e32 v7, v65, v16
	v_mul_f32_e32 v8, v67, v16
	v_permlane32_swap_b32_e32 v26, v6
	v_permlane32_swap_b32_e32 v27, v7
	v_permlane32_swap_b32_e32 v28, v44
	v_permlane32_swap_b32_e32 v29, v8
.LBB0_820:
	s_and_b64 vcc, exec, s[0:1]
	s_cbranch_vccz .LBB0_854
	v_readfirstlane_b32 s0, v208
	s_lshr_b32 s34, s0, 6
	s_mul_i32 s0, s12, 0x1800
	s_add_u32 s25, s92, s0
	s_addc_u32 s31, s93, 0
	s_add_u32 s50, s25, 0x400
	s_addc_u32 s51, s31, 0
	s_lshl_b32 s0, s97, 16
	v_readlane_b32 s1, v247, 34
	s_add_u32 s0, s1, s0
	v_readlane_b32 s1, v247, 35
	s_addc_u32 s1, s1, 0
	s_lshl_b32 s10, s12, 1
	s_add_u32 s10, s0, s10
	s_addc_u32 s11, s1, 0
	s_lshl_b32 s95, s16, 8
	s_lshl_b32 s94, s34, 5
	s_add_i32 s0, s94, s95
	v_or_b32_e32 v80, s0, v15
	s_waitcnt vmcnt(0)
	v_add_u32_e32 v4, s12, v80
	v_mov_b64_e32 v[2:3], s[92:93]
	v_mad_u64_u32 v[2:3], s[0:1], v4, s45, v[2:3]
	s_lshl_b32 s0, s97, 1
	s_mov_b32 s1, s9
	v_lshl_add_u64 v[2:3], v[2:3], 0, s[0:1]
	s_lshl_b32 s1, s16, 2
	s_add_i32 s1, s1, 4
	s_or_b32 s24, s95, 0xc0
	v_mov_b32_e32 v179, v17
	s_add_u32 s30, s25, s0
	v_lshl_add_u64 v[18:19], v[2:3], 0, v[178:179]
	s_addc_u32 s31, s31, 0
	global_load_dwordx4 v[2:5], v[18:19], off
	global_load_dwordx4 v[6:9], v[18:19], off offset:32
	global_load_dwordx4 v[10:13], v[18:19], off offset:64
	global_load_dwordx4 v[68:71], v[18:19], off offset:96
	global_load_dwordx4 v[238:241], v[18:19], off offset:3072
	global_load_dwordx4 v[242:245], v[18:19], off offset:3104
	global_load_dwordx4 v[248:251], v[18:19], off offset:3136
	global_load_dwordx4 v[252:255], v[18:19], off offset:3168
	v_add_u32_e32 v16, s24, v147
	v_mov_b64_e32 v[18:19], s[30:31]
	v_mad_u64_u32 v[18:19], s[30:31], v16, s45, v[18:19]
	v_lshlrev_b32_e32 v16, 1, v140
	v_lshl_add_u64 v[18:19], v[18:19], 0, v[16:17]
	global_load_dwordx4 v[72:75], v[18:19], off offset:1024
	v_lshlrev_b32_e32 v18, 1, v146
	v_mov_b32_e32 v19, v17
	v_lshl_add_u64 v[18:19], s[10:11], 0, v[18:19]
	s_mov_b32 s25, s9
	v_lshl_add_u64 v[18:19], s[24:25], 1, v[18:19]
	v_lshl_add_u64 v[18:19], v[18:19], 0, v[16:17]
	global_load_dwordx4 v[76:79], v[18:19], off
	s_lshl_b32 s10, s34, 2
	v_add_u32_e32 v18, v204, v142
	s_add_i32 s49, s10, 0
	s_lshl_b32 s10, s17, 11
	s_mov_b32 s11, s9
	s_lshl_b32 s24, s16, 3
	s_mov_b32 s17, s9
	s_add_i32 s49, s49, 0x10000
	v_lshl_add_u64 v[82:83], v[166:167], 0, s[10:11]
	s_add_i32 s97, s34, s24
	s_lshl_b64 s[10:11], s[16:17], 9
	s_add_u32 s10, s8, s10
	v_mov_b32_e32 v34, v17
	v_mov_b32_e32 v35, v17
	s_addc_u32 s11, 0, s11
	v_mov_b32_e32 v36, v17
	v_mov_b32_e32 v37, v17
	v_mov_b32_e32 v38, v17
	v_mov_b32_e32 v39, v17
	v_mov_b32_e32 v40, v17
	v_mov_b32_e32 v41, v17
	v_mov_b32_e32 v42, v17
	v_mov_b32_e32 v43, v17
	v_mov_b32_e32 v44, v17
	v_mov_b32_e32 v45, v17
	v_mov_b32_e32 v46, v17
	v_mov_b32_e32 v47, v17
	v_mov_b32_e32 v48, v17
	v_mov_b32_e32 v49, v17
	s_mov_b32 s44, s85
	s_mov_b32 s85, 1
	v_lshl_add_u64 v[84:85], v[174:175], 0, s[10:11]
	v_or_b32_e32 v51, s95, v145
	s_add_i32 s8, s94, 0xffffff20
	s_addk_i32 s94, 0xff40
	s_or_b32 s24, s24, 6
	s_addk_i32 s95, 0x140
	s_mov_b32 s25, 0
	s_mov_b64 s[30:31], 0
	v_mov_b32_e32 v87, 0
	s_waitcnt vmcnt(1)
	ds_write_b128 v18, v[72:75]
	v_add_u32_e32 v18, v206, v207
	v_add_u32_e32 v18, 0x2000, v18
	s_waitcnt vmcnt(0)
	ds_write2_b64 v18, v[76:77], v[78:79] offset0:128 offset1:130
	v_mov_b64_e32 v[18:19], v[34:35]
	v_mov_b64_e32 v[20:21], v[36:37]
	v_mov_b64_e32 v[22:23], v[38:39]
	v_mov_b64_e32 v[24:25], v[40:41]
	v_mov_b64_e32 v[26:27], v[42:43]
	v_mov_b64_e32 v[28:29], v[44:45]
	v_mov_b64_e32 v[30:31], v[46:47]
	v_mov_b64_e32 v[32:33], v[48:49]
	s_waitcnt lgkmcnt(0)
	s_barrier
	s_branch .LBB0_851

.LBB0_853:
	v_mov_b64_e32 v[4:5], s[92:93]
	v_ashrrev_i32_e32 v81, 31, v80
	v_lshl_add_u64 v[2:3], v[80:81], 0, s[12:13]
	v_mad_u64_u32 v[4:5], s[10:11], v2, s45, v[4:5]
	v_mad_i32_i24 v5, v3, s45, v5
	s_mov_b32 s1, s9
	v_readlane_b32 s10, v247, 37
	v_lshl_add_u64 v[4:5], v[4:5], 0, s[0:1]
	v_lshlrev_b64 v[2:3], 11, v[2:3]
	v_readlane_b32 s11, v247, 38
	v_mov_b32_e32 v179, v17
	v_permlane32_swap_b32_e32 v34, v38
	v_lshl_add_u64 v[56:57], s[10:11], 0, v[2:3]
	v_lshl_add_u64 v[2:3], v[4:5], 0, v[178:179]
	s_waitcnt vmcnt(0)
	v_mov_b32_e32 v52, v238
	v_mov_b32_e32 v53, v239
	v_mov_b32_e32 v54, v240
	v_mov_b32_e32 v55, v241
	v_mov_b32_e32 v10, v242
	v_mov_b32_e32 v11, v243
	v_mov_b32_e32 v12, v244
	v_mov_b32_e32 v13, v245
	v_mov_b32_e32 v6, v248
	v_mov_b32_e32 v7, v249
	v_mov_b32_e32 v8, v250
	v_mov_b32_e32 v9, v251
	s_nop 0
	v_mov_b32_e32 v2, v252
	v_mov_b32_e32 v3, v253
	v_mov_b32_e32 v4, v254
	v_mov_b32_e32 v5, v255
	v_lshl_add_u64 v[56:57], v[56:57], 0, s[0:1]
	v_lshl_add_u64 v[84:85], v[56:57], 0, v[178:179]
	v_permlane32_swap_b32_e32 v35, v39
	v_permlane32_swap_b32_e32 v36, v40
	v_permlane32_swap_b32_e32 v37, v41
	s_mov_b32 s85, s44
	s_waitcnt vmcnt(3)
	v_lshlrev_b32_e32 v56, 16, v52
	v_mul_f32_e32 v16, 0xbfb8aa3b, v56
	v_exp_f32_e32 v16, v16
	v_and_b32_e32 v57, 0xffff0000, v52
	v_lshlrev_b32_e32 v52, 16, v53
	v_and_b32_e32 v53, 0xffff0000, v53
	v_add_f32_e32 v16, 1.0, v16
	v_rcp_f32_e32 v58, v16
	v_mul_f32_e32 v16, 0xbfb8aa3b, v57
	v_exp_f32_e32 v16, v16
	v_pk_mul_f32 v[34:35], v[56:57], v[34:35]
	v_pk_mul_f32 v[36:37], v[52:53], v[36:37]
	v_add_f32_e32 v16, 1.0, v16
	v_rcp_f32_e32 v59, v16
	v_mul_f32_e32 v16, 0xbfb8aa3b, v52
	v_exp_f32_e32 v16, v16
	v_lshlrev_b32_e32 v52, 16, v54
	v_pk_mul_f32 v[34:35], v[34:35], v[58:59]
	v_add_f32_e32 v16, 1.0, v16
	v_rcp_f32_e32 v56, v16
	v_mul_f32_e32 v16, 0xbfb8aa3b, v53
	v_exp_f32_e32 v16, v16
	v_and_b32_e32 v53, 0xffff0000, v54
	v_pk_mul_f32 v[38:39], v[52:53], v[38:39]
	v_cvt_pk_bf16_f32 v34, v34, v35
	v_add_f32_e32 v16, 1.0, v16
	v_rcp_f32_e32 v57, v16
	v_mul_f32_e32 v16, 0xbfb8aa3b, v52
	v_exp_f32_e32 v16, v16
	v_lshlrev_b32_e32 v52, 16, v55
	v_pk_mul_f32 v[36:37], v[56:57], v[36:37]
	v_add_f32_e32 v16, 1.0, v16
	v_rcp_f32_e32 v56, v16
	v_mul_f32_e32 v16, 0xbfb8aa3b, v53
	v_exp_f32_e32 v16, v16
	v_and_b32_e32 v53, 0xffff0000, v55
	v_cvt_pk_bf16_f32 v35, v36, v37
	v_pk_mul_f32 v[40:41], v[52:53], v[40:41]
	v_add_f32_e32 v16, 1.0, v16
	v_rcp_f32_e32 v57, v16
	v_mul_f32_e32 v16, 0xbfb8aa3b, v52
	v_exp_f32_e32 v16, v16
	v_pk_mul_f32 v[38:39], v[38:39], v[56:57]
	s_nop 0
	v_cvt_pk_bf16_f32 v36, v38, v39
	v_add_f32_e32 v16, 1.0, v16
	v_rcp_f32_e32 v54, v16
	v_mul_f32_e32 v16, 0xbfb8aa3b, v53
	v_exp_f32_e32 v16, v16
	s_waitcnt vmcnt(2)
	v_lshlrev_b32_e32 v38, 16, v10
	v_and_b32_e32 v39, 0xffff0000, v10
	v_mul_f32_e32 v10, 0xbfb8aa3b, v38
	v_add_f32_e32 v16, 1.0, v16
	v_rcp_f32_e32 v55, v16
	v_exp_f32_e32 v10, v10
	v_pk_mul_f32 v[40:41], v[54:55], v[40:41]
	v_add_f32_e32 v10, 1.0, v10
	v_cvt_pk_bf16_f32 v37, v40, v41
	v_rcp_f32_e32 v40, v10
	v_mul_f32_e32 v10, 0xbfb8aa3b, v39
	v_exp_f32_e32 v10, v10
	global_store_dwordx4 v[84:85], v[34:37], off
	v_add_f32_e32 v10, 1.0, v10
	v_rcp_f32_e32 v41, v10
	v_mov_b32_e32 v36, v46
	v_mov_b32_e32 v37, v47
	s_nop 0
	v_permlane32_swap_b32_e32 v42, v36
	v_permlane32_swap_b32_e32 v43, v37
	v_mov_b32_e32 v34, v48
	v_mov_b32_e32 v35, v49
	s_nop 0
	v_permlane32_swap_b32_e32 v44, v34
	v_permlane32_swap_b32_e32 v45, v35
	v_pk_mul_f32 v[42:43], v[38:39], v[42:43]
	v_lshlrev_b32_e32 v10, 16, v11
	v_and_b32_e32 v11, 0xffff0000, v11
	v_pk_mul_f32 v[38:39], v[40:41], v[42:43]
	v_mul_f32_e32 v16, 0xbfb8aa3b, v10
	v_pk_mul_f32 v[42:43], v[10:11], v[44:45]
	v_mul_f32_e32 v10, 0xbfb8aa3b, v11
	v_exp_f32_e32 v10, v10
	v_exp_f32_e32 v16, v16
	v_and_b32_e32 v11, 0xffff0000, v12
	v_mov_b32_e32 v44, v32
	v_add_f32_e32 v10, 1.0, v10
	v_rcp_f32_e32 v41, v10
	v_lshlrev_b32_e32 v10, 16, v12
	v_mul_f32_e32 v12, 0xbfb8aa3b, v10
	v_pk_mul_f32 v[36:37], v[10:11], v[36:37]
	v_mul_f32_e32 v10, 0xbfb8aa3b, v11
	v_add_f32_e32 v16, 1.0, v16
	v_exp_f32_e32 v10, v10
	v_rcp_f32_e32 v40, v16
	v_exp_f32_e32 v12, v12
	v_and_b32_e32 v11, 0xffff0000, v13
	v_add_f32_e32 v10, 1.0, v10
	v_pk_mul_f32 v[40:41], v[40:41], v[42:43]
	v_add_f32_e32 v12, 1.0, v12
	v_rcp_f32_e32 v43, v10
	v_lshlrev_b32_e32 v10, 16, v13
	v_rcp_f32_e32 v42, v12
	v_mul_f32_e32 v12, 0xbfb8aa3b, v10
	v_pk_mul_f32 v[34:35], v[10:11], v[34:35]
	v_mul_f32_e32 v10, 0xbfb8aa3b, v11
	v_exp_f32_e32 v12, v12
	v_exp_f32_e32 v10, v10
	v_pk_mul_f32 v[36:37], v[42:43], v[36:37]
	v_cvt_pk_bf16_f32 v11, v40, v41
	v_add_f32_e32 v12, 1.0, v12
	v_add_f32_e32 v10, 1.0, v10
	v_rcp_f32_e32 v12, v12
	v_rcp_f32_e32 v13, v10
	v_cvt_pk_bf16_f32 v10, v38, v39
	v_permlane32_swap_b32_e32 v28, v44
	v_pk_mul_f32 v[34:35], v[12:13], v[34:35]
	v_cvt_pk_bf16_f32 v12, v36, v37
	v_cvt_pk_bf16_f32 v13, v34, v35
	global_store_dwordx4 v[84:85], v[10:13], off offset:32
	s_nop 1
	v_mov_b32_e32 v10, v22
	s_waitcnt vmcnt(3)
	v_lshlrev_b32_e32 v22, 16, v6
	v_mov_b32_e32 v11, v23
	v_and_b32_e32 v23, 0xffff0000, v6
	v_mul_f32_e32 v6, 0xbfb8aa3b, v22
	v_exp_f32_e32 v6, v6
	v_mov_b32_e32 v12, v24
	v_mov_b32_e32 v13, v25
	s_nop 0
	v_permlane32_swap_b32_e32 v20, v12
	v_add_f32_e32 v6, 1.0, v6
	v_rcp_f32_e32 v24, v6
	v_mul_f32_e32 v6, 0xbfb8aa3b, v23
	v_exp_f32_e32 v6, v6
	v_permlane32_swap_b32_e32 v21, v13
	v_permlane32_swap_b32_e32 v18, v10
	v_add_f32_e32 v6, 1.0, v6
	v_rcp_f32_e32 v25, v6
	v_lshlrev_b32_e32 v6, 16, v7
	v_and_b32_e32 v7, 0xffff0000, v7
	v_mul_f32_e32 v16, 0xbfb8aa3b, v6
	v_pk_mul_f32 v[20:21], v[6:7], v[20:21]
	v_mul_f32_e32 v6, 0xbfb8aa3b, v7
	v_exp_f32_e32 v6, v6
	v_exp_f32_e32 v16, v16
	v_permlane32_swap_b32_e32 v19, v11
	v_add_f32_e32 v6, 1.0, v6
	v_pk_mul_f32 v[18:19], v[22:23], v[18:19]
	v_rcp_f32_e32 v23, v6
	v_lshlrev_b32_e32 v6, 16, v8
	v_and_b32_e32 v7, 0xffff0000, v8
	v_mul_f32_e32 v8, 0xbfb8aa3b, v6
	v_pk_mul_f32 v[10:11], v[6:7], v[10:11]
	v_mul_f32_e32 v6, 0xbfb8aa3b, v7
	v_add_f32_e32 v16, 1.0, v16
	v_exp_f32_e32 v6, v6
	v_rcp_f32_e32 v22, v16
	v_exp_f32_e32 v8, v8
	v_and_b32_e32 v7, 0xffff0000, v9
	v_add_f32_e32 v6, 1.0, v6
	v_pk_mul_f32 v[20:21], v[22:23], v[20:21]
	v_add_f32_e32 v8, 1.0, v8
	v_rcp_f32_e32 v23, v6
	v_lshlrev_b32_e32 v6, 16, v9
	v_rcp_f32_e32 v22, v8
	v_mul_f32_e32 v8, 0xbfb8aa3b, v6
	v_pk_mul_f32 v[12:13], v[6:7], v[12:13]
	v_mul_f32_e32 v6, 0xbfb8aa3b, v7
	v_exp_f32_e32 v8, v8
	v_exp_f32_e32 v6, v6
	v_pk_mul_f32 v[18:19], v[24:25], v[18:19]
	v_pk_mul_f32 v[10:11], v[22:23], v[10:11]
	v_add_f32_e32 v8, 1.0, v8
	v_add_f32_e32 v6, 1.0, v6
	v_rcp_f32_e32 v8, v8
	v_rcp_f32_e32 v9, v6
	v_cvt_pk_bf16_f32 v6, v18, v19
	v_cvt_pk_bf16_f32 v7, v20, v21
	v_pk_mul_f32 v[12:13], v[8:9], v[12:13]
	v_cvt_pk_bf16_f32 v8, v10, v11
	v_cvt_pk_bf16_f32 v9, v12, v13
	global_store_dwordx4 v[84:85], v[6:9], off offset:64
	s_nop 1
	v_mov_b32_e32 v6, v30
	v_mov_b32_e32 v7, v31
	v_mov_b32_e32 v8, v33
	v_permlane32_swap_b32_e32 v26, v6
	v_permlane32_swap_b32_e32 v27, v7
	v_permlane32_swap_b32_e32 v29, v8
